# phase_post row loop: the six 16-byte row loads (q heads, k, indexer q, indexer k) requested together at the top of the row ahead of the position load; one wait instead of five load-wait steps
# speedup vs baseline: 1.0059x; 1.0007x over previous
.LBB0_644:
	v_ashrrev_i32_e32 v43, 31, v42
	v_lshlrev_b64 v[200:201], 12, v[42:43]
	v_lshl_add_u64 v[200:201], v[48:49], 0, v[200:201]
	global_load_dwordx4 v[176:179], v[200:201], off
	global_load_dwordx4 v[180:183], v[200:201], off offset:16
	v_lshlrev_b64 v[202:203], 8, v[42:43]
	v_lshl_add_u64 v[202:203], v[50:51], 0, v[202:203]
	global_load_dwordx4 v[184:187], v[202:203], off
	global_load_dwordx4 v[188:191], v[202:203], off offset:16
	v_lshlrev_b64 v[204:205], 10, v[42:43]
	v_lshl_add_u64 v[204:205], v[52:53], 0, v[204:205]
	global_load_dwordx4 v[192:195], v[204:205], off
	v_lshlrev_b64 v[206:207], 7, v[42:43]
	v_lshl_add_u64 v[206:207], v[54:55], 0, v[206:207]
	global_load_dwordx4 v[196:199], v[206:207], off
	s_and_saveexec_b64 s[0:1], vcc
	s_cbranch_execz .LBB0_646
	v_readlane_b32 s64, v253, 22
	v_readlane_b32 s66, v253, 24
	v_readlane_b32 s67, v253, 25
	v_readlane_b32 s65, v253, 23
	v_readlane_b32 s68, v253, 26
	v_lshl_add_u64 v[0:1], v[42:43], 2, s[66:67]
	global_load_dword v2, v[0:1], off
	s_nop 0
	global_load_dwordx2 v[0:1], v[46:47], off
	v_readlane_b32 s69, v253, 27
	v_readlane_b32 s70, v253, 28
	v_readlane_b32 s71, v253, 29
	v_readlane_b32 s72, v253, 30
	v_readlane_b32 s73, v253, 31
	v_readlane_b32 s74, v253, 32
	v_readlane_b32 s75, v253, 33
	v_readlane_b32 s76, v253, 34
	v_readlane_b32 s77, v253, 35
	v_readlane_b32 s78, v253, 36
	v_readlane_b32 s79, v253, 37
	s_waitcnt vmcnt(0)
	v_cvt_f64_i32_e32 v[2:3], v2
	v_mul_f64 v[4:5], v[0:1], v[2:3]
	v_rndne_f64_e32 v[4:5], v[4:5]
	v_fma_f64 v[0:1], v[0:1], v[2:3], -v[4:5]
	v_cvt_f32_f64_e32 v1, v[0:1]
	v_cos_f32_e32 v0, v1
	v_sin_f32_e32 v1, v1
	v_add_u32_e32 v2, v108, v44
	ds_write_b64 v2, v[0:1]
.LBB0_646:
	s_or_b64 exec, exec, s[0:1]
	v_lshlrev_b64 v[0:1], 12, v[42:43]
	s_waitcnt lgkmcnt(0)
	s_waitcnt vmcnt(0)
	v_lshl_add_u64 v[80:81], v[48:49], 0, v[0:1]
	v_mov_b32_e32 v0, v176
	v_mov_b32_e32 v1, v177
	v_mov_b32_e32 v2, v178
	v_mov_b32_e32 v3, v179
	v_mov_b32_e32 v64, v180
	v_mov_b32_e32 v65, v181
	v_mov_b32_e32 v66, v182
	v_mov_b32_e32 v67, v183
	v_lshlrev_b32_e32 v68, 16, v0
	v_and_b32_e32 v69, 0xffff0000, v0
	v_lshlrev_b32_e32 v62, 16, v1
	v_and_b32_e32 v63, 0xffff0000, v1
	v_lshlrev_b32_e32 v60, 16, v2
	v_and_b32_e32 v61, 0xffff0000, v2
	v_lshlrev_b32_e32 v58, 16, v3
	v_and_b32_e32 v59, 0xffff0000, v3
	v_pk_mul_f32 v[2:3], v[68:69], v[68:69]
	v_lshlrev_b32_e32 v56, 16, v64
	s_waitcnt lgkmcnt(0)
	v_and_b32_e32 v57, 0xffff0000, v64
	v_lshlrev_b32_e32 v6, 16, v65
	v_and_b32_e32 v7, 0xffff0000, v65
	v_pk_mul_f32 v[64:65], v[62:63], v[62:63]
	v_add_f32_e32 v2, v2, v3
	v_add_f32_e32 v2, v2, v64
	v_lshlrev_b32_e32 v4, 16, v66
	v_and_b32_e32 v5, 0xffff0000, v66
	v_lshlrev_b32_e32 v0, 16, v67
	v_and_b32_e32 v1, 0xffff0000, v67
	v_pk_mul_f32 v[66:67], v[60:61], v[60:61]
	v_add_f32_e32 v2, v65, v2
	v_add_f32_e32 v2, v66, v2
	v_pk_mul_f32 v[70:71], v[58:59], v[58:59]
	v_add_f32_e32 v2, v67, v2
	v_add_f32_e32 v2, v70, v2
	v_pk_mul_f32 v[72:73], v[56:57], v[56:57]
	v_add_f32_e32 v2, v71, v2
	v_add_f32_e32 v2, v72, v2
	v_pk_mul_f32 v[74:75], v[6:7], v[6:7]
	v_add_f32_e32 v2, v73, v2
	v_add_f32_e32 v2, v74, v2
	v_pk_mul_f32 v[76:77], v[4:5], v[4:5]
	v_add_f32_e32 v2, v75, v2
	v_add_f32_e32 v2, v76, v2
	v_pk_mul_f32 v[78:79], v[0:1], v[0:1]
	v_add_f32_e32 v2, v77, v2
	v_add_f32_e32 v2, v78, v2
	v_add_f32_e32 v2, v79, v2
	ds_bpermute_b32 v3, v45, v2
	s_waitcnt lgkmcnt(0)
	v_add_f32_e32 v2, v2, v3
	ds_bpermute_b32 v3, v109, v2
	s_waitcnt lgkmcnt(0)
	v_add_f32_e32 v2, v2, v3
	ds_bpermute_b32 v3, v110, v2
	s_waitcnt lgkmcnt(0)
	v_add_f32_e32 v2, v2, v3
	v_fmamk_f32 v2, v2, 0x3c000000, v216
	v_mul_f32_e32 v3, 0x4b800000, v2
	v_cmp_gt_f32_e64 s[0:1], s45, v2
	s_nop 1
	v_cndmask_b32_e64 v2, v2, v3, s[0:1]
	v_rsq_f32_e32 v2, v2
	s_nop 0
	v_mul_f32_e32 v3, 0x45800000, v2
	v_cndmask_b32_e64 v64, v2, v3, s[0:1]
	v_mov_b32_e32 v65, v64
	v_pk_mul_f32 v[2:3], v[64:65], v[68:69] op_sel_hi:[0,1]
	v_pk_mul_f32 v[96:97], v[22:23], v[2:3]
	v_pk_mul_f32 v[0:1], v[64:65], v[0:1]
	ds_bpermute_b32 v3, v45, v96
	v_pk_mul_f32 v[82:83], v[10:11], v[0:1]
	ds_read_b64 v[0:1], v108
	v_pk_mul_f32 v[62:63], v[64:65], v[62:63]
	v_pk_mul_f32 v[60:61], v[64:65], v[60:61]
	v_pk_mul_f32 v[58:59], v[64:65], v[58:59]
	v_pk_mul_f32 v[56:57], v[64:65], v[56:57]
	v_pk_mul_f32 v[6:7], v[64:65], v[6:7]
	v_pk_mul_f32 v[4:5], v[64:65], v[4:5]
	v_pk_mul_f32 v[94:95], v[24:25], v[62:63]
	v_pk_mul_f32 v[92:93], v[18:19], v[60:61]
	v_pk_mul_f32 v[90:91], v[20:21], v[58:59]
	v_pk_mul_f32 v[88:89], v[12:13], v[56:57]
	v_pk_mul_f32 v[86:87], v[14:15], v[6:7]
	v_pk_mul_f32 v[84:85], v[8:9], v[4:5]
	v_cmp_lt_i32_e64 s[0:1], 0, v16
	s_and_saveexec_b64 s[22:23], s[0:1]
	s_xor_b64 s[22:23], exec, s[22:23]
	s_cbranch_execz .LBB0_650
	v_cmp_eq_u32_e64 s[0:1], 1, v16
	s_and_saveexec_b64 s[24:25], s[0:1]
	s_cbranch_execz .LBB0_649
	v_mov_b32_e32 v2, v96
	s_waitcnt lgkmcnt(0)
	v_pk_mul_f32 v[2:3], v[0:1], v[2:3]
	s_nop 0
	v_add_f32_e32 v96, v3, v2

.LBB0_742:
	s_or_b64 exec, exec, s[0:1]
	v_cvt_pk_bf16_f32 v96, v96, v97
	v_cvt_pk_bf16_f32 v97, v94, v95
	v_cvt_pk_bf16_f32 v98, v92, v93
	s_waitcnt lgkmcnt(1)
	v_cvt_pk_bf16_f32 v99, v90, v91
	v_cvt_pk_bf16_f32 v88, v88, v89
	v_cvt_pk_bf16_f32 v89, v86, v87
	v_cvt_pk_bf16_f32 v90, v84, v85
	v_cvt_pk_bf16_f32 v91, v82, v83
	global_store_dwordx4 v[80:81], v[96:99], off
	global_store_dwordx4 v[80:81], v[88:91], off offset:16
	v_lshlrev_b64 v[80:81], 8, v[42:43]
	v_lshl_add_u64 v[80:81], v[50:51], 0, v[80:81]
	v_mov_b32_e32 v90, 0
	v_mov_b32_e32 v91, 0
	v_mov_b32_e32 v82, 0
	v_mov_b32_e32 v83, 0
	v_mov_b32_e32 v84, 0
	v_mov_b32_e32 v85, 0
	v_mov_b32_e32 v86, 0
	v_mov_b32_e32 v87, 0
	v_mov_b32_e32 v88, 0
	v_mov_b32_e32 v89, 0
	v_mov_b32_e32 v100, 0
	v_mov_b32_e32 v101, 0
	v_mov_b32_e32 v102, 0
	v_mov_b32_e32 v103, 0
	v_mov_b32_e32 v104, 0
	v_mov_b32_e32 v105, 0
	s_and_saveexec_b64 s[0:1], s[4:5]
	s_cbranch_execz .LBB0_744
	v_mov_b32_e32 v84, v184
	v_mov_b32_e32 v85, v185
	v_mov_b32_e32 v86, v186
	v_mov_b32_e32 v87, v187
	v_mov_b32_e32 v92, v188
	v_mov_b32_e32 v93, v189
	v_mov_b32_e32 v94, v190
	v_mov_b32_e32 v95, v191
	v_lshlrev_b32_e32 v90, 16, v84
	v_and_b32_e32 v91, 0xffff0000, v84
	v_lshlrev_b32_e32 v82, 16, v85
	v_and_b32_e32 v83, 0xffff0000, v85
	v_lshlrev_b32_e32 v84, 16, v86
	v_and_b32_e32 v85, 0xffff0000, v86
	v_lshlrev_b32_e32 v86, 16, v87
	v_and_b32_e32 v87, 0xffff0000, v87
	v_lshlrev_b32_e32 v88, 16, v92
	v_and_b32_e32 v89, 0xffff0000, v92
	v_lshlrev_b32_e32 v100, 16, v93
	v_and_b32_e32 v101, 0xffff0000, v93
	v_lshlrev_b32_e32 v102, 16, v94
	v_and_b32_e32 v103, 0xffff0000, v94
	v_lshlrev_b32_e32 v104, 16, v95
	v_and_b32_e32 v105, 0xffff0000, v95

.LBB0_840:
	s_or_b64 exec, exec, s[0:1]
	s_waitcnt lgkmcnt(0)
	v_lshlrev_b64 v[0:1], 10, v[42:43]
	v_lshl_add_u64 v[58:59], v[52:53], 0, v[0:1]
	v_mov_b32_e32 v4, v192
	v_mov_b32_e32 v5, v193
	v_mov_b32_e32 v6, v194
	v_mov_b32_e32 v7, v195
	ds_read_b64 v[56:57], v108 offset:128
	v_cmp_lt_i32_e64 s[0:1], 0, v16
	v_lshlrev_b32_e32 v60, 16, v4
	ds_bpermute_b32 v61, v45, v60
	v_and_b32_e32 v1, 0xffff0000, v4
	v_lshlrev_b32_e32 v2, 16, v5
	v_and_b32_e32 v3, 0xffff0000, v5
	v_lshlrev_b32_e32 v4, 16, v6
	v_and_b32_e32 v5, 0xffff0000, v6
	v_lshlrev_b32_e32 v6, 16, v7
	v_and_b32_e32 v7, 0xffff0000, v7
	s_and_saveexec_b64 s[22:23], s[0:1]
	s_xor_b64 s[22:23], exec, s[22:23]
	s_cbranch_execz .LBB0_844
	v_cmp_eq_u32_e64 s[0:1], 1, v16
	s_and_saveexec_b64 s[24:25], s[0:1]
	s_cbranch_execz .LBB0_843
	s_waitcnt lgkmcnt(0)
	v_pk_mul_f32 v[60:61], v[56:57], v[60:61]
	s_nop 0
	v_add_f32_e32 v60, v60, v61

.LBB0_888:
	s_or_b64 exec, exec, s[0:1]
	v_cvt_pk_bf16_f32 v0, v0, v1
	v_cvt_pk_bf16_f32 v1, v2, v3
	v_cvt_pk_bf16_f32 v2, v4, v5
	v_cvt_pk_bf16_f32 v3, v6, v7
	global_store_dwordx4 v[58:59], v[0:3], off
	s_nop 1
	v_lshlrev_b64 v[0:1], 7, v[42:43]
	v_lshl_add_u64 v[58:59], v[54:55], 0, v[0:1]
	v_mov_b32_e32 v0, 0
	v_mov_b32_e32 v1, v0
	v_mov_b32_e32 v2, v0
	v_mov_b32_e32 v3, v0
	v_mov_b32_e32 v4, v0
	v_mov_b32_e32 v5, v0
	v_mov_b32_e32 v6, v0
	v_mov_b32_e32 v7, v0
	s_and_saveexec_b64 s[0:1], s[4:5]
	s_cbranch_execz .LBB0_890
	v_mov_b32_e32 v4, v196
	v_mov_b32_e32 v5, v197
	v_mov_b32_e32 v6, v198
	v_mov_b32_e32 v7, v199
	v_lshlrev_b32_e32 v0, 16, v4
	v_and_b32_e32 v1, 0xffff0000, v4
	v_lshlrev_b32_e32 v2, 16, v5
	v_and_b32_e32 v3, 0xffff0000, v5
	v_lshlrev_b32_e32 v4, 16, v6
	v_and_b32_e32 v5, 0xffff0000, v6
	v_lshlrev_b32_e32 v6, 16, v7
	v_and_b32_e32 v7, 0xffff0000, v7
